# sample attention: workgroups enter the tile loop a quarter tile apart (s_sleep by blockIdx&3) so that HBM request bursts of the 256 CUs interleave
# speedup vs baseline: 1.0365x; 1.0044x over previous
.LBB0_779:
	s_and_b32 s0, s14, 3
.Lsa_stagger:
	s_cmp_eq_u32 s0, 0
	s_cbranch_scc1 .Lsa_stagger_done
	s_sleep 44
	s_sub_u32 s0, s0, 1
	s_branch .Lsa_stagger
